# attention mainloop: all eight K-fragment ds_read_b128 issued up front into free VGPRs with counted lgkmcnt waits (one exposed LDS latency per tile instead of four); on top of v68
# speedup vs baseline: 1.0054x; 1.0012x over previous
; #define LAS __attribute__((address_space(3)))
; #define AT_LOAD(kr_, vr_, i_) do { const int i1_ = (i_), loc_ = i1_ < nloc; const int krow0_ = loc_ ? MC + b * SEQ + t0 + 32 * (klo + i1_) : b * CTXL + 32 * (i1_ - nloc), vcol0_ = loc_ ? CTXL + t0 + 32 * (klo + i1_) : 32 * (i1_ - nloc); \
;             kr_ = *(const u32x4*)(kg0 + (size_t)krow0_ * 256); vr_ = *(const u32x4*)(vg0 + vcol0_); } while (0)
; #define AT_STORE(kr_, vr_, buf_) do { LAS unsigned char* bp_ = lds + (buf_) * AT_TILE; *(LAS u32x4*)(bp_ + krow_s * AT_KROW + kc_s * 16) = kr_; \
;             *(LAS u32x2*)(bp_ + AT_KB + vrow_s * AT_VROW + vc_s * 16) = (u32x2){vr_.x, vr_.y}; *(LAS u32x2*)(bp_ + AT_KB + vrow_s * AT_VROW + vc_s * 16 + 8) = (u32x2){vr_.z, vr_.w}; } while (0)
; __device__ __forceinline__ void attn_tile(f32x16 (&O)[4], float& m_run, float& l_run, const bf16x8 (&qf)[8], const LAS unsigned char* kp, const LAS unsigned char* vp, int mode, int dq, float sc2, int half) {
;     f32x16 s;
; #pragma unroll
;     for (int i = 0; i < 16; ++i) s[i] = 0.f;
;     bf16x8 kf[8];
; #pragma unroll
;     for (int ks = 0; ks < 8; ++ks) kf[ks] = *(const LAS bf16x8*)(kp + 32 * ks);
;     s16x4 vlo[2][4], vhi[2][4];
; #pragma unroll
;     for (int s2 = 0; s2 < 2; ++s2)
; #pragma unroll
;         for (int dt = 0; dt < 4; ++dt) { const LAS unsigned char* vq = vp + (32 * dt) * AT_VROW + 32 * s2; vlo[s2][dt] = *(const LAS s16x4*)vq; vhi[s2][dt] = *(const LAS s16x4*)(vq + 16); }
; #pragma unroll
;     for (int ks = 0; ks < 8; ++ks) s = __builtin_amdgcn_mfma_f32_32x32x16_bf16(kf[ks], qf[ks], s, 0, 0, 0);
;     float tmax = -3.0e38f;
; #pragma unroll
;     for (int r = 0; r < 16; ++r) tmax = fmaxf(tmax, s[r]);
;     if (mode != 0) {
;         const int klo = mode == 1 ? dq - 128 : -100000, khi = mode == 2 ? dq + 128 : 100000;
;         tmax = -3.0e38f;
; #pragma unroll
;         for (int r = 0; r < 16; ++r) { const int key = (r & 3) + 8 * (r >> 2) + 4 * half; float t = s[r];
;             if (key < klo || key > khi) t = -1.0e30f;
;             s[r] = t; tmax = fmaxf(tmax, t); }
; __device__ __forceinline__ void attn_phase(const Args& a, int layer, LAS unsigned char* lds, int tid, int wave, int lane) {
;     ...
;         u32x4 kregA, vregA, kregB, vregB;
;         AT_LOAD(kregA, vregA, 0); AT_STORE(kregA, vregA, 0);
;         AT_LOAD(kregA, vregA, 1);
;         __syncthreads();
.LBB0_906:
	s_and_b64 s[34:35], exec, s[38:39]
	s_cselect_b32 s34, s22, s13
	s_add_i32 s31, s31, s34
	s_and_b64 s[34:35], exec, s[38:39]
	s_cselect_b32 s34, s14, s16
	s_lshl_b32 s31, s31, 5
	s_add_i32 s34, s31, s34
	s_ashr_i32 s35, s34, 31
	s_lshl_b64 s[34:35], s[34:35], 9
	v_lshl_add_u64 v[66:67], v[182:183], 0, s[34:35]
	s_ashr_i32 s31, s30, 31
	v_lshl_add_u64 v[68:69], s[30:31], 1, v[184:185]
	global_load_dwordx4 v[122:125], v[66:67], off
	global_load_dwordx4 v[126:129], v[68:69], off
	s_cmp_gt_i32 s29, s15
	s_cselect_b64 s[30:31], -1, 0
	s_add_i32 s34, s25, s29
	s_add_i32 s35, s34, 4
	s_cmp_lt_u32 s35, 9
	s_cselect_b64 s[38:39], -1, 0
	s_or_b64 s[38:39], s[30:31], s[38:39]
	s_andn2_b64 vcc, exec, s[38:39]
	s_cbranch_vccnz .LBB0_914
	v_add_u32_e32 v138, v188, v186
	ds_read_b128 v[66:69], v138
	ds_read_b128 v[130:133], v138 offset:32
	ds_read_b128 v[214:217], v138 offset:64
	ds_read_b128 v[134:137], v138 offset:96
	ds_read_b128 v[218:221], v138 offset:128
	ds_read_b128 v[222:225], v138 offset:160
	ds_read_b128 v[226:229], v138 offset:192
	ds_read_b128 v[210:213], v138 offset:224
	s_cmp_lg_u32 s27, s29
	s_cselect_b64 s[38:39], -1, 0
	s_cmp_lg_u32 s26, s29
	s_waitcnt lgkmcnt(7)
	v_mfma_f32_32x32x16_bf16 v[66:81], v[66:69], v[82:85], 0
	s_cselect_b64 s[40:41], -1, 0
	s_and_b64 s[48:49], s[40:41], s[38:39]
	s_or_b64 s[48:49], s[30:31], s[48:49]
	s_and_b64 vcc, exec, s[48:49]
	s_waitcnt lgkmcnt(6)
	v_mfma_f32_32x32x16_bf16 v[66:81], v[130:133], v[86:89], v[66:81]
	s_waitcnt lgkmcnt(5)
	v_mfma_f32_32x32x16_bf16 v[66:81], v[214:217], v[90:93], v[66:81]
	s_waitcnt lgkmcnt(4)
	v_mfma_f32_32x32x16_bf16 v[66:81], v[134:137], v[94:97], v[66:81]
	s_waitcnt lgkmcnt(3)
	v_mfma_f32_32x32x16_bf16 v[66:81], v[218:221], v[98:101], v[66:81]
	s_waitcnt lgkmcnt(2)
	v_mfma_f32_32x32x16_bf16 v[66:81], v[222:225], v[102:105], v[66:81]
	v_add_u32_e32 v134, v179, v187
	v_add_u32_e32 v135, 0x2000, v134
	ds_read2_b64 v[158:161], v135 offset0:64 offset1:66
	ds_read2_b64 v[142:145], v135 offset0:68 offset1:70
	v_add_u32_e32 v135, 0x2800, v134
	ds_read2_b64 v[154:157], v135 offset0:96 offset1:98
	s_waitcnt lgkmcnt(4)
	v_mfma_f32_32x32x16_bf16 v[66:81], v[226:229], v[106:109], v[66:81]
	v_add_u32_e32 v130, 0x3000, v134
	v_add_u32_e32 v131, 0x3800, v134
	ds_read2_b64 v[150:153], v130 offset0:128 offset1:130
	ds_read2_b64 v[146:149], v131 offset0:160 offset1:162
	ds_read2_b64 v[138:141], v135 offset0:100 offset1:102
	ds_read2_b64 v[134:137], v130 offset0:132 offset1:134
	ds_read2_b64 v[130:133], v131 offset0:164 offset1:166
	s_waitcnt lgkmcnt(8)
	v_mfma_f32_32x32x16_bf16 v[66:81], v[210:213], v[110:113], v[66:81]
	s_cbranch_vccnz .LBB0_909
	v_cndmask_b32_e64 v180, v206, 0, s[30:31]
	v_add_u32_e32 v181, 0xffffff80, v180
	v_add_u32_e32 v180, 0x80, v180
	v_cndmask_b32_e64 v181, v181, v245, s[38:39]
	v_cndmask_b32_e64 v180, v180, v246, s[40:41]
	v_cmp_lt_i32_e32 vcc, v170, v181
	v_cmp_gt_i32_e64 s[38:39], v170, v180
	s_or_b64 vcc, vcc, s[38:39]
	s_nop 2
	v_cndmask_b32_e32 v66, v66, v247, vcc
	v_cmp_lt_i32_e32 vcc, v189, v181
	v_cmp_ge_i32_e64 s[38:39], v170, v180
	s_or_b64 vcc, vcc, s[38:39]
	v_cndmask_b32_e32 v67, v67, v247, vcc
	v_cmp_lt_i32_e32 vcc, v190, v181
	v_cmp_gt_i32_e64 s[38:39], v190, v180
	s_or_b64 vcc, vcc, s[38:39]
	v_cndmask_b32_e32 v68, v68, v247, vcc
	v_cmp_lt_i32_e32 vcc, v191, v181
	v_cmp_gt_i32_e64 s[38:39], v191, v180
	s_or_b64 vcc, vcc, s[38:39]
	v_cndmask_b32_e32 v69, v69, v247, vcc
	v_cmp_lt_i32_e32 vcc, v192, v181
	v_cmp_gt_i32_e64 s[38:39], v192, v180
	s_or_b64 vcc, vcc, s[38:39]
	v_cndmask_b32_e32 v70, v70, v247, vcc
	v_cmp_lt_i32_e32 vcc, v193, v181
	v_cmp_gt_i32_e64 s[38:39], v193, v180
	s_or_b64 vcc, vcc, s[38:39]
	v_cndmask_b32_e32 v71, v71, v247, vcc
	v_cmp_lt_i32_e32 vcc, v194, v181
	v_cmp_gt_i32_e64 s[38:39], v194, v180
	s_or_b64 vcc, vcc, s[38:39]
	v_cndmask_b32_e32 v72, v72, v247, vcc
	v_cmp_lt_i32_e32 vcc, v195, v181
	v_cmp_gt_i32_e64 s[38:39], v195, v180
	s_or_b64 vcc, vcc, s[38:39]
	v_cndmask_b32_e32 v73, v73, v247, vcc
	v_cmp_lt_i32_e32 vcc, v196, v181
	v_cmp_gt_i32_e64 s[38:39], v196, v180
	s_or_b64 vcc, vcc, s[38:39]
	v_cndmask_b32_e32 v74, v74, v247, vcc
	v_cmp_lt_i32_e32 vcc, v197, v181
	v_cmp_gt_i32_e64 s[38:39], v197, v180
	s_or_b64 vcc, vcc, s[38:39]
	v_cndmask_b32_e32 v75, v75, v247, vcc
	v_cmp_lt_i32_e32 vcc, v198, v181
	v_cmp_gt_i32_e64 s[38:39], v198, v180
	s_or_b64 vcc, vcc, s[38:39]
	v_cndmask_b32_e32 v76, v76, v247, vcc
	v_cmp_lt_i32_e32 vcc, v199, v181
	v_cmp_gt_i32_e64 s[38:39], v199, v180
	s_or_b64 vcc, vcc, s[38:39]
	v_cndmask_b32_e32 v77, v77, v247, vcc
	v_cmp_lt_i32_e32 vcc, v200, v181
	v_cmp_gt_i32_e64 s[38:39], v200, v180
	s_or_b64 vcc, vcc, s[38:39]
	v_max3_f32 v209, v66, s62, v67
	v_cndmask_b32_e32 v78, v78, v247, vcc
	v_cmp_lt_i32_e32 vcc, v201, v181
	v_cmp_gt_i32_e64 s[38:39], v201, v180
	v_max3_f32 v209, v209, v68, v69
	s_or_b64 vcc, vcc, s[38:39]
	v_max3_f32 v209, v209, v70, v71
	v_cndmask_b32_e32 v79, v79, v247, vcc
	v_cmp_lt_i32_e32 vcc, v202, v181
	v_cmp_gt_i32_e64 s[38:39], v202, v180
	v_max3_f32 v209, v209, v72, v73
	s_or_b64 vcc, vcc, s[38:39]
	v_max3_f32 v209, v209, v74, v75
	v_cndmask_b32_e32 v80, v80, v247, vcc
	v_cmp_lt_i32_e32 vcc, v203, v181
	v_cmp_gt_i32_e64 s[38:39], v203, v180
	v_max3_f32 v209, v209, v76, v77
	s_or_b64 vcc, vcc, s[38:39]
	v_max3_f32 v209, v209, v78, v79
	v_cndmask_b32_e32 v81, v81, v247, vcc
	v_max3_f32 v209, v209, v80, v81
	s_branch .LBB0_910

; #define LAS __attribute__((address_space(3)))
; #define AT_LOAD(kr_, vr_, i_) do { const int i1_ = (i_), loc_ = i1_ < nloc; const int krow0_ = loc_ ? MC + b * SEQ + t0 + 32 * (klo + i1_) : b * CTXL + 32 * (i1_ - nloc), vcol0_ = loc_ ? CTXL + t0 + 32 * (klo + i1_) : 32 * (i1_ - nloc); \
;             kr_ = *(const u32x4*)(kg0 + (size_t)krow0_ * 256); vr_ = *(const u32x4*)(vg0 + vcol0_); } while (0)
; #define AT_STORE(kr_, vr_, buf_) do { LAS unsigned char* bp_ = lds + (buf_) * AT_TILE; *(LAS u32x4*)(bp_ + krow_s * AT_KROW + kc_s * 16) = kr_; \
;             *(LAS u32x2*)(bp_ + AT_KB + vrow_s * AT_VROW + vc_s * 16) = (u32x2){vr_.x, vr_.y}; *(LAS u32x2*)(bp_ + AT_KB + vrow_s * AT_VROW + vc_s * 16 + 8) = (u32x2){vr_.z, vr_.w}; } while (0)
; __device__ __forceinline__ void attn_tile(f32x16 (&O)[4], float& m_run, float& l_run, const bf16x8 (&qf)[8], const LAS unsigned char* kp, const LAS unsigned char* vp, int mode, int dq, float sc2, int half) {
;     f32x16 s;
; #pragma unroll
;     for (int i = 0; i < 16; ++i) s[i] = 0.f;
;     bf16x8 kf[8];
; #pragma unroll
;     for (int ks = 0; ks < 8; ++ks) kf[ks] = *(const LAS bf16x8*)(kp + 32 * ks);
;     s16x4 vlo[2][4], vhi[2][4];
; #pragma unroll
;     for (int s2 = 0; s2 < 2; ++s2)
; #pragma unroll
;         for (int dt = 0; dt < 4; ++dt) { const LAS unsigned char* vq = vp + (32 * dt) * AT_VROW + 32 * s2; vlo[s2][dt] = *(const LAS s16x4*)vq; vhi[s2][dt] = *(const LAS s16x4*)(vq + 16); }
; #pragma unroll
;     for (int ks = 0; ks < 8; ++ks) s = __builtin_amdgcn_mfma_f32_32x32x16_bf16(kf[ks], qf[ks], s, 0, 0, 0);
;     float tmax = -3.0e38f;
; #pragma unroll
;     for (int r = 0; r < 16; ++r) tmax = fmaxf(tmax, s[r]);
;     if (mode != 0) {
;         const int klo = mode == 1 ? dq - 128 : -100000, khi = mode == 2 ? dq + 128 : 100000;
;         tmax = -3.0e38f;
; #pragma unroll
;         for (int r = 0; r < 16; ++r) { const int key = (r & 3) + 8 * (r >> 2) + 4 * half; float t = s[r];
;             if (key < klo || key > khi) t = -1.0e30f;
;             s[r] = t; tmax = fmaxf(tmax, t); }
; __device__ __forceinline__ void attn_phase(const Args& a, int layer, LAS unsigned char* lds, int tid, int wave, int lane) {
;     ...
;         u32x4 kregA, vregA, kregB, vregB;
;         AT_LOAD(kregA, vregA, 0); AT_STORE(kregA, vregA, 0);
;         AT_LOAD(kregA, vregA, 1);
;         __syncthreads();
.LBB0_921:
	s_and_b64 s[40:41], exec, s[38:39]
	s_cselect_b32 s35, s22, s13
	s_add_i32 s31, s31, s35
	s_and_b64 s[38:39], exec, s[38:39]
	s_cselect_b32 s35, s14, s16
	s_lshl_b32 s31, s31, 5
	s_add_i32 s38, s31, s35
	s_ashr_i32 s39, s38, 31
	s_lshl_b64 s[38:39], s[38:39], 9
	v_lshl_add_u64 v[66:67], v[182:183], 0, s[38:39]
	s_ashr_i32 s31, s30, 31
	v_lshl_add_u64 v[68:69], s[30:31], 1, v[184:185]
	global_load_dwordx4 v[114:117], v[66:67], off
	global_load_dwordx4 v[118:121], v[68:69], off
	s_cmp_ge_i32 s29, s15
	s_cselect_b64 s[30:31], -1, 0
	s_add_i32 s34, s34, 5
	s_cmp_lt_u32 s34, 9
	s_cselect_b64 s[34:35], -1, 0
	s_or_b64 s[34:35], s[30:31], s[34:35]
	s_andn2_b64 vcc, exec, s[34:35]
	s_cbranch_vccnz .LBB0_929
	v_add_u32_e32 v138, v188, v186
	ds_read_b128 v[66:69], v138 offset:17920
	ds_read_b128 v[130:133], v138 offset:17952
	ds_read_b128 v[214:217], v138 offset:17984
	ds_read_b128 v[134:137], v138 offset:18016
	ds_read_b128 v[218:221], v138 offset:18048
	ds_read_b128 v[222:225], v138 offset:18080
	ds_read_b128 v[226:229], v138 offset:18112
	ds_read_b128 v[210:213], v138 offset:18144
	s_cmp_lg_u32 s24, s29
	s_cselect_b64 s[38:39], -1, 0
	s_cmp_lg_u32 s23, s29
	s_waitcnt lgkmcnt(7)
	v_mfma_f32_32x32x16_bf16 v[66:81], v[66:69], v[82:85], 0
	s_cselect_b64 s[40:41], -1, 0
	s_and_b64 s[34:35], s[40:41], s[38:39]
	s_or_b64 s[34:35], s[30:31], s[34:35]
	s_and_b64 vcc, exec, s[34:35]
	s_waitcnt lgkmcnt(6)
	v_mfma_f32_32x32x16_bf16 v[66:81], v[130:133], v[86:89], v[66:81]
	s_waitcnt lgkmcnt(5)
	v_mfma_f32_32x32x16_bf16 v[66:81], v[214:217], v[90:93], v[66:81]
	s_waitcnt lgkmcnt(4)
	v_mfma_f32_32x32x16_bf16 v[66:81], v[134:137], v[94:97], v[66:81]
	s_waitcnt lgkmcnt(3)
	v_mfma_f32_32x32x16_bf16 v[66:81], v[218:221], v[98:101], v[66:81]
	s_waitcnt lgkmcnt(2)
	v_mfma_f32_32x32x16_bf16 v[66:81], v[222:225], v[102:105], v[66:81]
	v_add_u32_e32 v134, v179, v187
	v_add_u32_e32 v135, 0x6800, v134
	ds_read2_b64 v[158:161], v135 offset1:2
	ds_read2_b64 v[142:145], v135 offset0:4 offset1:6
	v_add_u32_e32 v135, 0x7000, v134
	ds_read2_b64 v[154:157], v135 offset0:32 offset1:34
	s_waitcnt lgkmcnt(4)
	v_mfma_f32_32x32x16_bf16 v[66:81], v[226:229], v[106:109], v[66:81]
	v_add_u32_e32 v130, 0x7800, v134
	v_add_u32_e32 v131, 0x8000, v134
	ds_read2_b64 v[150:153], v130 offset0:64 offset1:66
	ds_read2_b64 v[146:149], v131 offset0:96 offset1:98
	ds_read2_b64 v[138:141], v135 offset0:36 offset1:38
	ds_read2_b64 v[134:137], v130 offset0:68 offset1:70
	ds_read2_b64 v[130:133], v131 offset0:100 offset1:102
	s_waitcnt lgkmcnt(8)
	v_mfma_f32_32x32x16_bf16 v[66:81], v[210:213], v[110:113], v[66:81]
	s_cbranch_vccnz .LBB0_924
	v_subrev_u32_e32 v180, 32, v206
	v_cndmask_b32_e64 v180, v180, 0, s[30:31]
	v_add_u32_e32 v181, 0xffffff80, v180
	v_add_u32_e32 v180, 0x80, v180
	v_cndmask_b32_e64 v181, v181, v245, s[38:39]
	v_cndmask_b32_e64 v180, v180, v246, s[40:41]
	v_cmp_lt_i32_e32 vcc, v170, v181
	v_cmp_gt_i32_e64 s[38:39], v170, v180
	s_or_b64 vcc, vcc, s[38:39]
	s_nop 1
	v_cndmask_b32_e32 v66, v66, v247, vcc
	v_cmp_lt_i32_e32 vcc, v189, v181
	v_cmp_ge_i32_e64 s[38:39], v170, v180
	s_or_b64 vcc, vcc, s[38:39]
	v_cndmask_b32_e32 v67, v67, v247, vcc
	v_cmp_lt_i32_e32 vcc, v190, v181
	v_cmp_gt_i32_e64 s[38:39], v190, v180
	s_or_b64 vcc, vcc, s[38:39]
	v_cndmask_b32_e32 v68, v68, v247, vcc
	v_cmp_lt_i32_e32 vcc, v191, v181
	v_cmp_gt_i32_e64 s[38:39], v191, v180
	s_or_b64 vcc, vcc, s[38:39]
	v_cndmask_b32_e32 v69, v69, v247, vcc
	v_cmp_lt_i32_e32 vcc, v192, v181
	v_cmp_gt_i32_e64 s[38:39], v192, v180
	s_or_b64 vcc, vcc, s[38:39]
	v_cndmask_b32_e32 v70, v70, v247, vcc
	v_cmp_lt_i32_e32 vcc, v193, v181
	v_cmp_gt_i32_e64 s[38:39], v193, v180
	s_or_b64 vcc, vcc, s[38:39]
	v_cndmask_b32_e32 v71, v71, v247, vcc
	v_cmp_lt_i32_e32 vcc, v194, v181
	v_cmp_gt_i32_e64 s[38:39], v194, v180
	s_or_b64 vcc, vcc, s[38:39]
	v_cndmask_b32_e32 v72, v72, v247, vcc
	v_cmp_lt_i32_e32 vcc, v195, v181
	v_cmp_gt_i32_e64 s[38:39], v195, v180
	s_or_b64 vcc, vcc, s[38:39]
	v_cndmask_b32_e32 v73, v73, v247, vcc
	v_cmp_lt_i32_e32 vcc, v196, v181
	v_cmp_gt_i32_e64 s[38:39], v196, v180
	s_or_b64 vcc, vcc, s[38:39]
	v_cndmask_b32_e32 v74, v74, v247, vcc
	v_cmp_lt_i32_e32 vcc, v197, v181
	v_cmp_gt_i32_e64 s[38:39], v197, v180
	s_or_b64 vcc, vcc, s[38:39]
	v_cndmask_b32_e32 v75, v75, v247, vcc
	v_cmp_lt_i32_e32 vcc, v198, v181
	v_cmp_gt_i32_e64 s[38:39], v198, v180
	s_or_b64 vcc, vcc, s[38:39]
	v_cndmask_b32_e32 v76, v76, v247, vcc
	v_cmp_lt_i32_e32 vcc, v199, v181
	v_cmp_gt_i32_e64 s[38:39], v199, v180
	s_or_b64 vcc, vcc, s[38:39]
	v_cndmask_b32_e32 v77, v77, v247, vcc
	v_cmp_lt_i32_e32 vcc, v200, v181
	v_cmp_gt_i32_e64 s[38:39], v200, v180
	s_or_b64 vcc, vcc, s[38:39]
	v_max3_f32 v209, v66, s62, v67
	v_cndmask_b32_e32 v78, v78, v247, vcc
	v_cmp_lt_i32_e32 vcc, v201, v181
	v_cmp_gt_i32_e64 s[38:39], v201, v180
	v_max3_f32 v209, v209, v68, v69
	s_or_b64 vcc, vcc, s[38:39]
	v_max3_f32 v209, v209, v70, v71
	v_cndmask_b32_e32 v79, v79, v247, vcc
	v_cmp_lt_i32_e32 vcc, v202, v181
	v_cmp_gt_i32_e64 s[38:39], v202, v180
	v_max3_f32 v209, v209, v72, v73
	s_or_b64 vcc, vcc, s[38:39]
	v_max3_f32 v209, v209, v74, v75
	v_cndmask_b32_e32 v80, v80, v247, vcc
	v_cmp_lt_i32_e32 vcc, v203, v181
	v_cmp_gt_i32_e64 s[38:39], v203, v180
	v_max3_f32 v209, v209, v76, v77
	s_or_b64 vcc, vcc, s[38:39]
	v_max3_f32 v209, v209, v78, v79
	v_cndmask_b32_e32 v81, v81, v247, vcc
	v_max3_f32 v209, v209, v80, v81
	s_branch .LBB0_925
